# E4: rebalance LDS-DMA issue 4+4 per super-phase (A tiles staged in SP1), vmcnt 8/6
# baseline (speedup 1.0000x reference)
.LBB0_294:
	s_add_i32 s22, s10, 2
	s_add_u32 s23, s2, 0x80
	s_addc_u32 s11, s3, 0
	s_add_i32 s41, 0, 0x10000
	s_cmp_eq_u32 s75, s10
	s_cselect_b32 s11, s83, s11
	s_cselect_b32 s10, s82, s23
	v_add_u32_e32 v0, s41, v153
	s_cselect_b32 s45, s95, s21
	s_cselect_b32 s44, s94, s20
	s_add_i32 s23, 0, 0x14000
	ds_read_b128 v[130:133], v0
	ds_read_b128 v[134:137], v0 offset:1024
	ds_read_b128 v[160:163], v0 offset:2048
	ds_read_b128 v[164:167], v0 offset:3072
	v_add_u32_e32 v0, s23, v153
	ds_read_b128 v[168:171], v0
	ds_read_b128 v[172:175], v0 offset:1024
	ds_read_b128 v[202:205], v0 offset:2048
	ds_read_b128 v[206:209], v0 offset:3072
	s_mov_b32 m0, s26
	ds_read_b128 v[210:213], v201
	ds_read_b128 v[214:217], v201 offset:1024
	ds_read_b128 v[218:221], v201 offset:2048
	ds_read_b128 v[222:225], v201 offset:3072
	ds_read_b128 v[226:229], v201 offset:4096
	ds_read_b128 v[230:233], v201 offset:5120
	ds_read_b128 v[234:237], v201 offset:6144
	ds_read_b128 v[238:241], v201 offset:7168
	global_load_lds_dwordx4 v144, s[2:3]
	s_mov_b32 m0, s27
	s_nop 0
	global_load_lds_dwordx4 v148, s[2:3]
	s_add_i32 m0, s29, 0xc000
	s_nop 0
	global_load_lds_dwordx4 v156, s[2:3]
	s_add_i32 m0, s29, 0xe000
	s_nop 0
	global_load_lds_dwordx4 v158, s[2:3]
	s_waitcnt vmcnt(8)
	s_waitcnt lgkmcnt(0)
	s_barrier
	s_setprio 1
	s_waitcnt lgkmcnt(0)
	v_mfma_f32_16x16x32_bf16 v[126:129], v[130:133], v[210:213], v[126:129]
	v_mfma_f32_16x16x32_bf16 v[122:125], v[160:163], v[210:213], v[122:125]
	v_mfma_f32_16x16x32_bf16 v[110:113], v[130:133], v[218:221], v[110:113]
	v_mfma_f32_16x16x32_bf16 v[106:109], v[160:163], v[218:221], v[106:109]
	v_mfma_f32_16x16x32_bf16 v[94:97], v[130:133], v[226:229], v[94:97]
	v_mfma_f32_16x16x32_bf16 v[90:93], v[160:163], v[226:229], v[90:93]
	v_mfma_f32_16x16x32_bf16 v[78:81], v[130:133], v[234:237], v[78:81]
	v_mfma_f32_16x16x32_bf16 v[74:77], v[160:163], v[234:237], v[74:77]
	v_mfma_f32_16x16x32_bf16 v[126:129], v[134:137], v[214:217], v[126:129]
	v_mfma_f32_16x16x32_bf16 v[122:125], v[164:167], v[214:217], v[122:125]
	v_mfma_f32_16x16x32_bf16 v[110:113], v[134:137], v[222:225], v[110:113]
	v_mfma_f32_16x16x32_bf16 v[106:109], v[164:167], v[222:225], v[106:109]
	v_mfma_f32_16x16x32_bf16 v[94:97], v[134:137], v[230:233], v[94:97]
	v_mfma_f32_16x16x32_bf16 v[90:93], v[164:167], v[230:233], v[90:93]
	v_mfma_f32_16x16x32_bf16 v[78:81], v[134:137], v[238:241], v[78:81]
	v_mfma_f32_16x16x32_bf16 v[74:77], v[164:167], v[238:241], v[74:77]
	s_setprio 0
	s_setprio 1
	v_mfma_f32_16x16x32_bf16 v[118:121], v[168:171], v[210:213], v[118:121]
	v_mfma_f32_16x16x32_bf16 v[114:117], v[202:205], v[210:213], v[114:117]
	v_mfma_f32_16x16x32_bf16 v[102:105], v[168:171], v[218:221], v[102:105]
	v_mfma_f32_16x16x32_bf16 v[98:101], v[202:205], v[218:221], v[98:101]
	v_mfma_f32_16x16x32_bf16 v[86:89], v[168:171], v[226:229], v[86:89]
	v_mfma_f32_16x16x32_bf16 v[82:85], v[202:205], v[226:229], v[82:85]
	v_mfma_f32_16x16x32_bf16 v[70:73], v[168:171], v[234:237], v[70:73]
	v_mfma_f32_16x16x32_bf16 v[66:69], v[202:205], v[234:237], v[66:69]
	v_mfma_f32_16x16x32_bf16 v[118:121], v[172:175], v[214:217], v[118:121]
	v_mfma_f32_16x16x32_bf16 v[114:117], v[206:209], v[214:217], v[114:117]
	v_mfma_f32_16x16x32_bf16 v[102:105], v[172:175], v[222:225], v[102:105]
	v_mfma_f32_16x16x32_bf16 v[98:101], v[206:209], v[222:225], v[98:101]
	v_mfma_f32_16x16x32_bf16 v[86:89], v[172:175], v[230:233], v[86:89]
	v_mfma_f32_16x16x32_bf16 v[82:85], v[206:209], v[230:233], v[82:85]
	v_mfma_f32_16x16x32_bf16 v[70:73], v[172:175], v[238:241], v[70:73]
	v_mfma_f32_16x16x32_bf16 v[66:69], v[206:209], v[238:241], v[66:69]
	s_setprio 0
	s_barrier
	s_add_i32 s41, s41, s79
	s_mov_b32 m0, s41
	ds_read_b128 v[210:213], v201 offset:16384
	ds_read_b128 v[214:217], v201 offset:17408
	ds_read_b128 v[218:221], v201 offset:18432
	ds_read_b128 v[222:225], v201 offset:19456
	ds_read_b128 v[226:229], v201 offset:20480
	ds_read_b128 v[230:233], v201 offset:21504
	ds_read_b128 v[234:237], v201 offset:22528
	ds_read_b128 v[238:241], v201 offset:23552
	global_load_lds_dwordx4 v146, s[44:45]
	s_add_i32 m0, s41, 0x2000
	s_add_u32 s98, s44, 0x80
	s_addc_u32 s99, s45, 0
	global_load_lds_dwordx4 v150, s[44:45]
	s_add_u32 s44, s44, s76
	s_addc_u32 s45, s45, 0
	s_add_i32 s23, s23, s79
	s_mov_b32 m0, s23
	s_nop 0
	global_load_lds_dwordx4 v146, s[44:45]
	s_add_i32 m0, s23, 0x2000
	s_nop 0
	global_load_lds_dwordx4 v150, s[44:45]
	s_waitcnt vmcnt(6)
	s_waitcnt lgkmcnt(0)
	s_barrier
	s_setprio 1
	s_waitcnt lgkmcnt(0)
	v_mfma_f32_16x16x32_bf16 v[62:65], v[130:133], v[210:213], v[62:65]
	v_mfma_f32_16x16x32_bf16 v[58:61], v[160:163], v[210:213], v[58:61]
	v_mfma_f32_16x16x32_bf16 v[46:49], v[130:133], v[218:221], v[46:49]
	v_mfma_f32_16x16x32_bf16 v[42:45], v[160:163], v[218:221], v[42:45]
	v_mfma_f32_16x16x32_bf16 v[30:33], v[130:133], v[226:229], v[30:33]
	v_mfma_f32_16x16x32_bf16 v[26:29], v[160:163], v[226:229], v[26:29]
	v_mfma_f32_16x16x32_bf16 v[14:17], v[130:133], v[234:237], v[14:17]
	v_mfma_f32_16x16x32_bf16 v[10:13], v[160:163], v[234:237], v[10:13]
	v_mfma_f32_16x16x32_bf16 v[62:65], v[134:137], v[214:217], v[62:65]
	v_mfma_f32_16x16x32_bf16 v[58:61], v[164:167], v[214:217], v[58:61]
	v_mfma_f32_16x16x32_bf16 v[46:49], v[134:137], v[222:225], v[46:49]
	v_mfma_f32_16x16x32_bf16 v[42:45], v[164:167], v[222:225], v[42:45]
	v_mfma_f32_16x16x32_bf16 v[30:33], v[134:137], v[230:233], v[30:33]
	v_mfma_f32_16x16x32_bf16 v[26:29], v[164:167], v[230:233], v[26:29]
	v_mfma_f32_16x16x32_bf16 v[14:17], v[134:137], v[238:241], v[14:17]
	v_mfma_f32_16x16x32_bf16 v[10:13], v[164:167], v[238:241], v[10:13]
	s_setprio 0
	s_setprio 1
	v_mfma_f32_16x16x32_bf16 v[54:57], v[168:171], v[210:213], v[54:57]
	v_mfma_f32_16x16x32_bf16 v[50:53], v[202:205], v[210:213], v[50:53]
	v_mfma_f32_16x16x32_bf16 v[38:41], v[168:171], v[218:221], v[38:41]
	v_mfma_f32_16x16x32_bf16 v[34:37], v[202:205], v[218:221], v[34:37]
	v_mfma_f32_16x16x32_bf16 v[22:25], v[168:171], v[226:229], v[22:25]
	v_mfma_f32_16x16x32_bf16 v[18:21], v[202:205], v[226:229], v[18:21]
	v_mfma_f32_16x16x32_bf16 v[6:9], v[168:171], v[234:237], v[6:9]
	v_mfma_f32_16x16x32_bf16 v[2:5], v[202:205], v[234:237], v[2:5]
	v_mfma_f32_16x16x32_bf16 v[54:57], v[172:175], v[214:217], v[54:57]
	v_mfma_f32_16x16x32_bf16 v[50:53], v[206:209], v[214:217], v[50:53]
	v_mfma_f32_16x16x32_bf16 v[38:41], v[172:175], v[222:225], v[38:41]
	v_mfma_f32_16x16x32_bf16 v[34:37], v[206:209], v[222:225], v[34:37]
	v_mfma_f32_16x16x32_bf16 v[22:25], v[172:175], v[230:233], v[22:25]
	v_mfma_f32_16x16x32_bf16 v[18:21], v[206:209], v[230:233], v[18:21]
	v_mfma_f32_16x16x32_bf16 v[6:9], v[172:175], v[238:241], v[6:9]
	v_mfma_f32_16x16x32_bf16 v[2:5], v[206:209], v[238:241], v[2:5]
	s_setprio 0
	s_barrier
	s_add_i32 s23, 0, 0x18000
	v_add_u32_e32 v0, s23, v153
	s_add_i32 s41, 0, 0x1c000
	ds_read_b128 v[130:133], v0
	ds_read_b128 v[134:137], v0 offset:1024
	ds_read_b128 v[160:163], v0 offset:2048
	ds_read_b128 v[164:167], v0 offset:3072
	v_add_u32_e32 v0, s41, v153
	ds_read_b128 v[168:171], v0
	ds_read_b128 v[172:175], v0 offset:1024
	ds_read_b128 v[202:205], v0 offset:2048
	ds_read_b128 v[206:209], v0 offset:3072
	s_mov_b32 m0, s29
	ds_read_b128 v[210:213], v201 offset:32768
	ds_read_b128 v[214:217], v201 offset:33792
	ds_read_b128 v[218:221], v201 offset:34816
	ds_read_b128 v[222:225], v201 offset:35840
	ds_read_b128 v[226:229], v201 offset:36864
	ds_read_b128 v[230:233], v201 offset:37888
	ds_read_b128 v[234:237], v201 offset:38912
	ds_read_b128 v[238:241], v201 offset:39936
	global_load_lds_dwordx4 v144, s[10:11]
	s_mov_b32 m0, s93
	s_nop 0
	global_load_lds_dwordx4 v148, s[10:11]
	s_mov_b32 m0, s52
	s_nop 0
	global_load_lds_dwordx4 v156, s[10:11]
	s_mov_b32 m0, s53
	s_nop 0
	global_load_lds_dwordx4 v158, s[10:11]
	s_waitcnt vmcnt(8)
	s_waitcnt lgkmcnt(0)
	s_barrier
	s_setprio 1
	s_waitcnt lgkmcnt(0)
	v_mfma_f32_16x16x32_bf16 v[126:129], v[130:133], v[210:213], v[126:129]
	v_mfma_f32_16x16x32_bf16 v[122:125], v[160:163], v[210:213], v[122:125]
	v_mfma_f32_16x16x32_bf16 v[110:113], v[130:133], v[218:221], v[110:113]
	v_mfma_f32_16x16x32_bf16 v[106:109], v[160:163], v[218:221], v[106:109]
	v_mfma_f32_16x16x32_bf16 v[94:97], v[130:133], v[226:229], v[94:97]
	v_mfma_f32_16x16x32_bf16 v[90:93], v[160:163], v[226:229], v[90:93]
	v_mfma_f32_16x16x32_bf16 v[78:81], v[130:133], v[234:237], v[78:81]
	v_mfma_f32_16x16x32_bf16 v[74:77], v[160:163], v[234:237], v[74:77]
	v_mfma_f32_16x16x32_bf16 v[126:129], v[134:137], v[214:217], v[126:129]
	v_mfma_f32_16x16x32_bf16 v[122:125], v[164:167], v[214:217], v[122:125]
	v_mfma_f32_16x16x32_bf16 v[110:113], v[134:137], v[222:225], v[110:113]
	v_mfma_f32_16x16x32_bf16 v[106:109], v[164:167], v[222:225], v[106:109]
	v_mfma_f32_16x16x32_bf16 v[94:97], v[134:137], v[230:233], v[94:97]
	v_mfma_f32_16x16x32_bf16 v[90:93], v[164:167], v[230:233], v[90:93]
	v_mfma_f32_16x16x32_bf16 v[78:81], v[134:137], v[238:241], v[78:81]
	v_mfma_f32_16x16x32_bf16 v[74:77], v[164:167], v[238:241], v[74:77]
	s_setprio 0
	s_setprio 1
	v_mfma_f32_16x16x32_bf16 v[118:121], v[168:171], v[210:213], v[118:121]
	v_mfma_f32_16x16x32_bf16 v[114:117], v[202:205], v[210:213], v[114:117]
	v_mfma_f32_16x16x32_bf16 v[102:105], v[168:171], v[218:221], v[102:105]
	v_mfma_f32_16x16x32_bf16 v[98:101], v[202:205], v[218:221], v[98:101]
	v_mfma_f32_16x16x32_bf16 v[86:89], v[168:171], v[226:229], v[86:89]
	v_mfma_f32_16x16x32_bf16 v[82:85], v[202:205], v[226:229], v[82:85]
	v_mfma_f32_16x16x32_bf16 v[70:73], v[168:171], v[234:237], v[70:73]
	v_mfma_f32_16x16x32_bf16 v[66:69], v[202:205], v[234:237], v[66:69]
	v_mfma_f32_16x16x32_bf16 v[118:121], v[172:175], v[214:217], v[118:121]
	v_mfma_f32_16x16x32_bf16 v[114:117], v[206:209], v[214:217], v[114:117]
	v_mfma_f32_16x16x32_bf16 v[102:105], v[172:175], v[222:225], v[102:105]
	v_mfma_f32_16x16x32_bf16 v[98:101], v[206:209], v[222:225], v[98:101]
	v_mfma_f32_16x16x32_bf16 v[86:89], v[172:175], v[230:233], v[86:89]
	v_mfma_f32_16x16x32_bf16 v[82:85], v[206:209], v[230:233], v[82:85]
	v_mfma_f32_16x16x32_bf16 v[70:73], v[172:175], v[238:241], v[70:73]
	v_mfma_f32_16x16x32_bf16 v[66:69], v[206:209], v[238:241], v[66:69]
	s_setprio 0
	s_barrier
	s_add_i32 s10, s23, s79
	s_mov_b32 m0, s10
	ds_read_b128 v[210:213], v201 offset:49152
	ds_read_b128 v[214:217], v201 offset:50176
	ds_read_b128 v[218:221], v201 offset:51200
	ds_read_b128 v[222:225], v201 offset:52224
	ds_read_b128 v[226:229], v201 offset:53248
	ds_read_b128 v[230:233], v201 offset:54272
	ds_read_b128 v[234:237], v201 offset:55296
	ds_read_b128 v[238:241], v201 offset:56320
	global_load_lds_dwordx4 v146, s[98:99]
	s_add_i32 m0, s10, 0x2000
	s_add_i32 s10, s41, s79
	global_load_lds_dwordx4 v150, s[98:99]
	s_add_u32 s98, s98, s76
	s_addc_u32 s99, s99, 0
	s_mov_b32 m0, s10
	s_nop 0
	global_load_lds_dwordx4 v146, s[98:99]
	s_add_i32 m0, s10, 0x2000
	s_nop 0
	global_load_lds_dwordx4 v150, s[98:99]
	s_waitcnt vmcnt(6)
	s_waitcnt lgkmcnt(0)
	s_barrier
	s_setprio 1
	s_waitcnt lgkmcnt(0)
	v_mfma_f32_16x16x32_bf16 v[62:65], v[130:133], v[210:213], v[62:65]
	v_mfma_f32_16x16x32_bf16 v[58:61], v[160:163], v[210:213], v[58:61]
	v_mfma_f32_16x16x32_bf16 v[46:49], v[130:133], v[218:221], v[46:49]
	v_mfma_f32_16x16x32_bf16 v[42:45], v[160:163], v[218:221], v[42:45]
	v_mfma_f32_16x16x32_bf16 v[30:33], v[130:133], v[226:229], v[30:33]
	v_mfma_f32_16x16x32_bf16 v[26:29], v[160:163], v[226:229], v[26:29]
	v_mfma_f32_16x16x32_bf16 v[14:17], v[130:133], v[234:237], v[14:17]
	v_mfma_f32_16x16x32_bf16 v[10:13], v[160:163], v[234:237], v[10:13]
	v_mfma_f32_16x16x32_bf16 v[62:65], v[134:137], v[214:217], v[62:65]
	v_mfma_f32_16x16x32_bf16 v[58:61], v[164:167], v[214:217], v[58:61]
	v_mfma_f32_16x16x32_bf16 v[46:49], v[134:137], v[222:225], v[46:49]
	v_mfma_f32_16x16x32_bf16 v[42:45], v[164:167], v[222:225], v[42:45]
	v_mfma_f32_16x16x32_bf16 v[30:33], v[134:137], v[230:233], v[30:33]
	v_mfma_f32_16x16x32_bf16 v[26:29], v[164:167], v[230:233], v[26:29]
	v_mfma_f32_16x16x32_bf16 v[14:17], v[134:137], v[238:241], v[14:17]
	v_mfma_f32_16x16x32_bf16 v[10:13], v[164:167], v[238:241], v[10:13]
	s_setprio 0
	s_setprio 1
	v_mfma_f32_16x16x32_bf16 v[54:57], v[168:171], v[210:213], v[54:57]
	v_mfma_f32_16x16x32_bf16 v[50:53], v[202:205], v[210:213], v[50:53]
	v_mfma_f32_16x16x32_bf16 v[38:41], v[168:171], v[218:221], v[38:41]
	v_mfma_f32_16x16x32_bf16 v[34:37], v[202:205], v[218:221], v[34:37]
	v_mfma_f32_16x16x32_bf16 v[22:25], v[168:171], v[226:229], v[22:25]
	v_mfma_f32_16x16x32_bf16 v[18:21], v[202:205], v[226:229], v[18:21]
	v_mfma_f32_16x16x32_bf16 v[6:9], v[168:171], v[234:237], v[6:9]
	v_mfma_f32_16x16x32_bf16 v[2:5], v[202:205], v[234:237], v[2:5]
	v_mfma_f32_16x16x32_bf16 v[54:57], v[172:175], v[214:217], v[54:57]
	v_mfma_f32_16x16x32_bf16 v[50:53], v[206:209], v[214:217], v[50:53]
	v_mfma_f32_16x16x32_bf16 v[38:41], v[172:175], v[222:225], v[38:41]
	v_mfma_f32_16x16x32_bf16 v[34:37], v[206:209], v[222:225], v[34:37]
	v_mfma_f32_16x16x32_bf16 v[22:25], v[172:175], v[230:233], v[22:25]
	v_mfma_f32_16x16x32_bf16 v[18:21], v[206:209], v[230:233], v[18:21]
	v_mfma_f32_16x16x32_bf16 v[6:9], v[172:175], v[238:241], v[6:9]
	v_mfma_f32_16x16x32_bf16 v[2:5], v[206:209], v[238:241], v[2:5]
	s_setprio 0
	s_barrier
	s_add_u32 s2, s2, 0x100
	s_addc_u32 s3, s3, 0
	s_add_u32 s20, s20, 0x100
	s_addc_u32 s21, s21, 0
	s_cmp_ge_u32 s22, s63
	s_mov_b32 s10, s22
	s_cbranch_scc0 .LBB0_294
	v_readlane_b32 s2, v255, 24
	v_readlane_b32 s3, v255, 25
	s_and_b64 vcc, exec, s[2:3]
	s_cbranch_vccz .LBB0_297
	s_barrier
